# prenorm: loop unrolled by two, two row buffers, the row two ahead requested each iteration
# baseline (speedup 1.0000x reference)
.LBB0_67:
	s_or_b64 exec, exec, s[0:1]
	v_lshrrev_b32_e32 v196, 6, v188
	v_lshl_add_u32 v144, s2, 3, v196
	s_mov_b32 s10, 0x10000
	s_lshl_b32 s88, s3, 3
	v_ashrrev_i32_e32 v145, 31, v144
	v_and_b32_e32 v189, 63, v188
	s_barrier
	v_cmp_gt_i32_e64 s[4:5], s10, v144
	s_mov_b64 s[0:1], exec
	s_nop 0
	v_writelane_b32 v255, s4, 9
	s_nop 1
	v_writelane_b32 v255, s5, 10
	s_and_b64 s[4:5], s[0:1], s[4:5]
	s_mov_b64 exec, s[4:5]
	s_cbranch_execz .LBB0_70
	v_readlane_b32 s12, v254, 9
	v_readlane_b32 s13, v254, 10
	v_lshlrev_b64 v[0:1], 12, v[144:145]
	s_mov_b64 s[8:9], s[12:13]
	v_readlane_b32 s14, v254, 11
	v_readlane_b32 s15, v254, 12
	v_readlane_b32 s16, v254, 13
	v_readlane_b32 s17, v254, 14
	v_lshl_add_u64 v[0:1], s[8:9], 0, v[0:1]
	v_lshlrev_b32_e32 v32, 4, v189
	v_mov_b32_e32 v33, 0
	v_readlane_b32 s18, v254, 15
	v_readlane_b32 s19, v254, 16
	s_mov_b64 s[12:13], s[16:17]
	v_lshl_add_u64 v[4:5], v[0:1], 0, v[32:33]
	s_mov_b64 s[14:15], s[18:19]
	global_load_dwordx4 v[0:3], v[4:5], off offset:3072 nt
	global_load_dwordx4 v[8:11], v[4:5], off offset:2048 nt
	global_load_dwordx4 v[24:27], v[4:5], off offset:1024 nt
	global_load_dwordx4 v[28:31], v[4:5], off nt
	s_nop 0
	global_load_dwordx4 v[4:7], v32, s[14:15]
	global_load_dwordx4 v[12:15], v32, s[14:15] offset:1024
	global_load_dwordx4 v[16:19], v32, s[14:15] offset:2048
	global_load_dwordx4 v[20:23], v32, s[14:15] offset:3072
	v_lshl_add_u64 v[34:35], s[8:9], 0, v[32:33]
	v_mbcnt_lo_u32_b32 v32, -1, 0
	v_mbcnt_hi_u32_b32 v32, -1, v32
	v_and_b32_e32 v36, 64, v32
	v_add_u32_e32 v36, 64, v36
	v_xor_b32_e32 v37, 32, v32
	v_cmp_lt_i32_e32 vcc, v37, v36
	s_ashr_i32 s89, s88, 31
	s_lshl_b64 s[4:5], s[88:89], 11
	v_cndmask_b32_e32 v37, v32, v37, vcc
	v_lshlrev_b32_e32 v44, 2, v37
	v_xor_b32_e32 v37, 16, v32
	v_cmp_lt_i32_e32 vcc, v37, v36
	s_mov_b64 s[6:7], 0
	s_mov_b32 s11, 0xffff
	v_cndmask_b32_e32 v37, v32, v37, vcc
	v_lshlrev_b32_e32 v45, 2, v37
	v_xor_b32_e32 v37, 8, v32
	v_cmp_lt_i32_e32 vcc, v37, v36
	v_mov_b32_e32 v50, 0x358637bd
	s_mov_b32 s12, 0x800000
	v_cndmask_b32_e32 v37, v32, v37, vcc
	v_lshlrev_b32_e32 v46, 2, v37
	v_xor_b32_e32 v37, 4, v32
	v_cmp_lt_i32_e32 vcc, v37, v36
	s_mov_b64 s[8:9], 0x1000
	v_mov_b32_e32 v41, v144
	v_cndmask_b32_e32 v37, v32, v37, vcc
	v_lshlrev_b32_e32 v47, 2, v37
	v_xor_b32_e32 v37, 2, v32
	v_cmp_lt_i32_e32 vcc, v37, v36
	v_readlane_b32 s20, v254, 17
	v_readlane_b32 s21, v254, 18
	v_cndmask_b32_e32 v37, v32, v37, vcc
	v_lshlrev_b32_e32 v48, 2, v37
	v_xor_b32_e32 v37, 1, v32
	v_cmp_lt_i32_e32 vcc, v37, v36
	v_readlane_b32 s22, v254, 19
	v_readlane_b32 s23, v254, 20
	v_cndmask_b32_e32 v32, v32, v37, vcc
	v_lshlrev_b32_e32 v49, 2, v32
	v_lshlrev_b32_e32 v32, 2, v189
	v_lshlrev_b64 v[36:37], 11, v[144:145]
	v_or_b32_e32 v38, 0x100, v32
	v_or_b32_e32 v40, 0x200, v32
	v_or_b32_e32 v42, 0x300, v32
	v_lshl_or_b32 v36, v189, 3, v36
	v_lshl_add_u64 v[36:37], s[56:57], 0, v[36:37]
	v_lshlrev_b32_e32 v32, 2, v32
	v_lshlrev_b32_e32 v38, 2, v38
	v_lshlrev_b32_e32 v40, 2, v40
	v_lshlrev_b32_e32 v42, 2, v42
	v_readlane_b32 s24, v254, 21
	v_readlane_b32 s25, v254, 22
	v_readlane_b32 s26, v254, 23
	v_readlane_b32 s27, v254, 24
	v_add_u32_e32 v129, s88, v41
	v_cmp_gt_i32_e32 vcc, s10, v129
	v_cndmask_b32_e32 v132, v41, v129, vcc
	v_ashrrev_i32_e32 v133, 31, v132
	v_lshlrev_b64 v[132:133], 12, v[132:133]
	v_lshl_add_u64 v[132:133], v[34:35], 0, v[132:133]
	global_load_dwordx4 v[112:115], v[132:133], off nt
	global_load_dwordx4 v[116:119], v[132:133], off offset:1024 nt
	global_load_dwordx4 v[120:123], v[132:133], off offset:2048 nt
	global_load_dwordx4 v[124:127], v[132:133], off offset:3072 nt
	s_waitcnt vmcnt(4)
.LBB0_69:
	v_mov_b32_e32 v56, v29
	v_mov_b32_e32 v57, v25
	v_ashrrev_i32_e32 v43, 12, v41
	v_mov_b32_e32 v54, v9
	v_mov_b32_e32 v55, v1
	v_pk_mul_f32 v[72:73], v[56:57], v[56:57]
	v_mul_i32_i24_e32 v56, 0xc00, v43
	v_mov_b32_e32 v52, v8
	v_mov_b32_e32 v53, v0
	v_pk_mul_f32 v[54:55], v[54:55], v[54:55]
	v_ashrrev_i32_e32 v57, 31, v56
	v_pk_fma_f32 v[74:75], v[52:53], v[52:53], v[54:55]
	v_lshl_add_u64 v[52:53], v[56:57], 2, s[38:39]
	v_lshl_add_u64 v[76:77], v[52:53], 0, s[8:9]
	v_lshl_add_u64 v[78:79], v[52:53], 0, v[32:33]
	v_lshl_add_u64 v[56:57], v[76:77], 0, v[32:33]
	global_load_dwordx4 v[52:55], v[78:79], off
	s_nop 0
	global_load_dwordx4 v[84:87], v[56:57], off
	global_load_dwordx4 v[88:91], v[56:57], off offset:1024
	global_load_dwordx4 v[92:95], v[78:79], off offset:1024
	global_load_dwordx4 v[96:99], v[56:57], off offset:2048
	global_load_dwordx4 v[100:103], v[78:79], off offset:2048
	global_load_dwordx4 v[104:107], v[56:57], off offset:3072
	global_load_dwordx4 v[108:111], v[78:79], off offset:3072
	v_add_u32_e32 v129, s88, v41
	v_add_u32_e32 v129, s88, v129
	v_cmp_gt_i32_e32 vcc, s10, v129
	v_cndmask_b32_e32 v132, v41, v129, vcc
	v_ashrrev_i32_e32 v133, 31, v132
	v_lshlrev_b64 v[132:133], 12, v[132:133]
	v_lshl_add_u64 v[132:133], v[34:35], 0, v[132:133]
	global_load_dwordx4 v[148:151], v[132:133], off nt
	global_load_dwordx4 v[152:155], v[132:133], off offset:1024 nt
	global_load_dwordx4 v[156:159], v[132:133], off offset:2048 nt
	global_load_dwordx4 v[160:163], v[132:133], off offset:3072 nt
	v_mov_b32_e32 v68, v28
	v_mov_b32_e32 v69, v24
	v_mov_b32_e32 v64, v30
	v_mov_b32_e32 v65, v26
	v_pk_fma_f32 v[68:69], v[68:69], v[68:69], v[72:73]
	v_mov_b32_e32 v60, v10
	v_mov_b32_e32 v61, v2
	v_add_u32_e32 v51, s88, v41
	v_mov_b32_e32 v66, v31
	v_mov_b32_e32 v67, v27
	v_pk_fma_f32 v[64:65], v[64:65], v[64:65], v[68:69]
	v_mov_b32_e32 v62, v11
	v_mov_b32_e32 v63, v3
	v_cmp_gt_i32_e32 vcc, s10, v51
	v_pk_fma_f32 v[60:61], v[60:61], v[60:61], v[74:75]
	v_pk_fma_f32 v[82:83], v[66:67], v[66:67], v[64:65]
	v_mov_b32_e32 v39, v33
	v_cndmask_b32_e32 v70, v41, v51, vcc
	v_pk_fma_f32 v[80:81], v[62:63], v[62:63], v[60:61]
	v_add_f32_e32 v41, v82, v83
	v_lshl_add_u64 v[82:83], v[76:77], 0, v[38:39]
	v_add_f32_e32 v39, v41, v80
	v_add_f32_e32 v39, v39, v81
	ds_bpermute_b32 v41, v44, v39
	v_ashrrev_i32_e32 v71, 31, v70
	v_lshlrev_b64 v[70:71], 12, v[70:71]
	v_lshl_add_u64 v[72:73], v[34:35], 0, v[70:71]
	s_waitcnt lgkmcnt(0)
	v_add_f32_e32 v39, v39, v41
	ds_bpermute_b32 v41, v45, v39
	v_mov_b32_e32 v43, v33
	s_waitcnt lgkmcnt(0)
	v_add_f32_e32 v39, v39, v41
	ds_bpermute_b32 v41, v46, v39
	s_waitcnt lgkmcnt(0)
	v_add_f32_e32 v39, v39, v41
	ds_bpermute_b32 v41, v47, v39
	s_waitcnt lgkmcnt(0)
	v_add_f32_e32 v39, v39, v41
	ds_bpermute_b32 v41, v48, v39
	s_waitcnt lgkmcnt(0)
	v_add_f32_e32 v39, v39, v41
	ds_bpermute_b32 v41, v49, v39
	s_waitcnt lgkmcnt(0)
	v_add_f32_e32 v39, v39, v41
	v_fmamk_f32 v39, v39, 0x3a800000, v50
	v_mul_f32_e32 v41, 0x4b800000, v39
	v_cmp_gt_f32_e32 vcc, s12, v39
	s_waitcnt vmcnt(4)
	v_pk_add_f32 v[56:57], v[84:85], 1.0 op_sel_hi:[1,0]
	v_cndmask_b32_e32 v39, v39, v41, vcc
	v_rsq_f32_e32 v39, v39
	v_pk_add_f32 v[58:59], v[86:87], 1.0 op_sel_hi:[1,0]
	v_mul_f32_e32 v41, 0x45800000, v39
	v_cndmask_b32_e32 v80, v39, v41, vcc
	v_pk_mul_f32 v[28:29], v[28:29], v[80:81] op_sel_hi:[1,0]
	v_pk_mul_f32 v[30:31], v[30:31], v[80:81] op_sel_hi:[1,0]
	v_pk_mul_f32 v[28:29], v[4:5], v[28:29]
	v_pk_mul_f32 v[30:31], v[6:7], v[30:31]
	v_pk_fma_f32 v[28:29], v[56:57], v[28:29], v[52:53]
	v_pk_fma_f32 v[30:31], v[58:59], v[30:31], v[54:55]
	v_cvt_pk_bf16_f32 v28, v28, v29
	v_cvt_pk_bf16_f32 v29, v30, v31
	global_store_dwordx2 v[36:37], v[28:29], off
	v_pk_mul_f32 v[24:25], v[24:25], v[80:81] op_sel_hi:[1,0]
	v_pk_mul_f32 v[26:27], v[26:27], v[80:81] op_sel_hi:[1,0]
	v_pk_mul_f32 v[24:25], v[12:13], v[24:25]
	v_pk_mul_f32 v[26:27], v[14:15], v[26:27]
	v_mov_b32_e32 v41, v33
	v_lshl_add_u64 v[56:57], v[76:77], 0, v[40:41]
	v_pk_mul_f32 v[8:9], v[8:9], v[80:81] op_sel_hi:[1,0]
	v_pk_mul_f32 v[10:11], v[10:11], v[80:81] op_sel_hi:[1,0]
	v_pk_mul_f32 v[8:9], v[16:17], v[8:9]
	v_pk_mul_f32 v[10:11], v[18:19], v[10:11]
	v_pk_mul_f32 v[0:1], v[0:1], v[80:81] op_sel_hi:[1,0]
	v_pk_mul_f32 v[2:3], v[2:3], v[80:81] op_sel_hi:[1,0]
	v_cmp_lt_i32_e32 vcc, s11, v51
	v_mov_b32_e32 v41, v51
	s_or_b64 s[6:7], vcc, s[6:7]
	v_pk_add_f32 v[28:29], v[88:89], 1.0 op_sel_hi:[1,0]
	v_pk_add_f32 v[30:31], v[90:91], 1.0 op_sel_hi:[1,0]
	v_pk_fma_f32 v[24:25], v[24:25], v[28:29], v[92:93]
	v_pk_fma_f32 v[26:27], v[26:27], v[30:31], v[94:95]
	v_cvt_pk_bf16_f32 v24, v24, v25
	v_cvt_pk_bf16_f32 v25, v26, v27
	global_store_dwordx2 v[36:37], v[24:25], off offset:512
	v_lshl_add_u64 v[52:53], v[76:77], 0, v[42:43]
	v_pk_mul_f32 v[76:77], v[20:21], v[0:1]
	v_pk_add_f32 v[24:25], v[96:97], 1.0 op_sel_hi:[1,0]
	v_pk_add_f32 v[26:27], v[98:99], 1.0 op_sel_hi:[1,0]
	v_pk_fma_f32 v[8:9], v[8:9], v[24:25], v[100:101]
	v_pk_fma_f32 v[10:11], v[10:11], v[26:27], v[102:103]
	v_cvt_pk_bf16_f32 v8, v8, v9
	v_cvt_pk_bf16_f32 v9, v10, v11
	global_store_dwordx2 v[36:37], v[8:9], off offset:1024
	v_pk_mul_f32 v[78:79], v[22:23], v[2:3]
	v_pk_add_f32 v[52:53], v[104:105], 1.0 op_sel_hi:[1,0]
	v_pk_add_f32 v[54:55], v[106:107], 1.0 op_sel_hi:[1,0]
	v_pk_fma_f32 v[52:53], v[76:77], v[52:53], v[108:109]
	v_pk_fma_f32 v[54:55], v[78:79], v[54:55], v[110:111]
	v_cvt_pk_bf16_f32 v52, v52, v53
	v_cvt_pk_bf16_f32 v53, v54, v55
	global_store_dwordx2 v[36:37], v[52:53], off offset:1536
	v_lshl_add_u64 v[36:37], v[36:37], 0, s[4:5]
	v_mov_b32_e32 v0, v124
	v_mov_b32_e32 v1, v125
	v_mov_b32_e32 v30, v114
	v_mov_b32_e32 v31, v115
	v_mov_b32_e32 v28, v112
	v_mov_b32_e32 v29, v113
	v_mov_b32_e32 v26, v118
	v_mov_b32_e32 v27, v119
	v_mov_b32_e32 v24, v116
	v_mov_b32_e32 v25, v117
	v_mov_b32_e32 v10, v122
	v_mov_b32_e32 v11, v123
	v_mov_b32_e32 v8, v120
	v_mov_b32_e32 v9, v121
	v_mov_b32_e32 v2, v126
	v_mov_b32_e32 v3, v127
	s_andn2_b64 exec, exec, s[6:7]
	s_cbranch_execz .Lpn_exit
	v_mov_b32_e32 v56, v29
	v_mov_b32_e32 v57, v25
	v_ashrrev_i32_e32 v43, 12, v41
	v_mov_b32_e32 v54, v9
	v_mov_b32_e32 v55, v1
	v_pk_mul_f32 v[72:73], v[56:57], v[56:57]
	v_mul_i32_i24_e32 v56, 0xc00, v43
	v_mov_b32_e32 v52, v8
	v_mov_b32_e32 v53, v0
	v_pk_mul_f32 v[54:55], v[54:55], v[54:55]
	v_ashrrev_i32_e32 v57, 31, v56
	v_pk_fma_f32 v[74:75], v[52:53], v[52:53], v[54:55]
	v_lshl_add_u64 v[52:53], v[56:57], 2, s[38:39]
	v_lshl_add_u64 v[76:77], v[52:53], 0, s[8:9]
	v_lshl_add_u64 v[78:79], v[52:53], 0, v[32:33]
	v_lshl_add_u64 v[56:57], v[76:77], 0, v[32:33]
	global_load_dwordx4 v[52:55], v[78:79], off
	s_nop 0
	global_load_dwordx4 v[84:87], v[56:57], off
	global_load_dwordx4 v[88:91], v[56:57], off offset:1024
	global_load_dwordx4 v[92:95], v[78:79], off offset:1024
	global_load_dwordx4 v[96:99], v[56:57], off offset:2048
	global_load_dwordx4 v[100:103], v[78:79], off offset:2048
	global_load_dwordx4 v[104:107], v[56:57], off offset:3072
	global_load_dwordx4 v[108:111], v[78:79], off offset:3072
	v_add_u32_e32 v129, s88, v41
	v_add_u32_e32 v129, s88, v129
	v_cmp_gt_i32_e32 vcc, s10, v129
	v_cndmask_b32_e32 v132, v41, v129, vcc
	v_ashrrev_i32_e32 v133, 31, v132
	v_lshlrev_b64 v[132:133], 12, v[132:133]
	v_lshl_add_u64 v[132:133], v[34:35], 0, v[132:133]
	global_load_dwordx4 v[112:115], v[132:133], off nt
	global_load_dwordx4 v[116:119], v[132:133], off offset:1024 nt
	global_load_dwordx4 v[120:123], v[132:133], off offset:2048 nt
	global_load_dwordx4 v[124:127], v[132:133], off offset:3072 nt
	v_mov_b32_e32 v68, v28
	v_mov_b32_e32 v69, v24
	v_mov_b32_e32 v64, v30
	v_mov_b32_e32 v65, v26
	v_pk_fma_f32 v[68:69], v[68:69], v[68:69], v[72:73]
	v_mov_b32_e32 v60, v10
	v_mov_b32_e32 v61, v2
	v_add_u32_e32 v51, s88, v41
	v_mov_b32_e32 v66, v31
	v_mov_b32_e32 v67, v27
	v_pk_fma_f32 v[64:65], v[64:65], v[64:65], v[68:69]
	v_mov_b32_e32 v62, v11
	v_mov_b32_e32 v63, v3
	v_cmp_gt_i32_e32 vcc, s10, v51
	v_pk_fma_f32 v[60:61], v[60:61], v[60:61], v[74:75]
	v_pk_fma_f32 v[82:83], v[66:67], v[66:67], v[64:65]
	v_mov_b32_e32 v39, v33
	v_cndmask_b32_e32 v70, v41, v51, vcc
	v_pk_fma_f32 v[80:81], v[62:63], v[62:63], v[60:61]
	v_add_f32_e32 v41, v82, v83
	v_lshl_add_u64 v[82:83], v[76:77], 0, v[38:39]
	v_add_f32_e32 v39, v41, v80
	v_add_f32_e32 v39, v39, v81
	ds_bpermute_b32 v41, v44, v39
	v_ashrrev_i32_e32 v71, 31, v70
	v_lshlrev_b64 v[70:71], 12, v[70:71]
	v_lshl_add_u64 v[72:73], v[34:35], 0, v[70:71]
	s_waitcnt lgkmcnt(0)
	v_add_f32_e32 v39, v39, v41
	ds_bpermute_b32 v41, v45, v39
	v_mov_b32_e32 v43, v33
	s_waitcnt lgkmcnt(0)
	v_add_f32_e32 v39, v39, v41
	ds_bpermute_b32 v41, v46, v39
	s_waitcnt lgkmcnt(0)
	v_add_f32_e32 v39, v39, v41
	ds_bpermute_b32 v41, v47, v39
	s_waitcnt lgkmcnt(0)
	v_add_f32_e32 v39, v39, v41
	ds_bpermute_b32 v41, v48, v39
	s_waitcnt lgkmcnt(0)
	v_add_f32_e32 v39, v39, v41
	ds_bpermute_b32 v41, v49, v39
	s_waitcnt lgkmcnt(0)
	v_add_f32_e32 v39, v39, v41
	v_fmamk_f32 v39, v39, 0x3a800000, v50
	v_mul_f32_e32 v41, 0x4b800000, v39
	v_cmp_gt_f32_e32 vcc, s12, v39
	s_waitcnt vmcnt(4)
	v_pk_add_f32 v[56:57], v[84:85], 1.0 op_sel_hi:[1,0]
	v_cndmask_b32_e32 v39, v39, v41, vcc
	v_rsq_f32_e32 v39, v39
	v_pk_add_f32 v[58:59], v[86:87], 1.0 op_sel_hi:[1,0]
	v_mul_f32_e32 v41, 0x45800000, v39
	v_cndmask_b32_e32 v80, v39, v41, vcc
	v_pk_mul_f32 v[28:29], v[28:29], v[80:81] op_sel_hi:[1,0]
	v_pk_mul_f32 v[30:31], v[30:31], v[80:81] op_sel_hi:[1,0]
	v_pk_mul_f32 v[28:29], v[4:5], v[28:29]
	v_pk_mul_f32 v[30:31], v[6:7], v[30:31]
	v_pk_fma_f32 v[28:29], v[56:57], v[28:29], v[52:53]
	v_pk_fma_f32 v[30:31], v[58:59], v[30:31], v[54:55]
	v_cvt_pk_bf16_f32 v28, v28, v29
	v_cvt_pk_bf16_f32 v29, v30, v31
	global_store_dwordx2 v[36:37], v[28:29], off
	v_pk_mul_f32 v[24:25], v[24:25], v[80:81] op_sel_hi:[1,0]
	v_pk_mul_f32 v[26:27], v[26:27], v[80:81] op_sel_hi:[1,0]
	v_pk_mul_f32 v[24:25], v[12:13], v[24:25]
	v_pk_mul_f32 v[26:27], v[14:15], v[26:27]
	v_mov_b32_e32 v41, v33
	v_lshl_add_u64 v[56:57], v[76:77], 0, v[40:41]
	v_pk_mul_f32 v[8:9], v[8:9], v[80:81] op_sel_hi:[1,0]
	v_pk_mul_f32 v[10:11], v[10:11], v[80:81] op_sel_hi:[1,0]
	v_pk_mul_f32 v[8:9], v[16:17], v[8:9]
	v_pk_mul_f32 v[10:11], v[18:19], v[10:11]
	v_pk_mul_f32 v[0:1], v[0:1], v[80:81] op_sel_hi:[1,0]
	v_pk_mul_f32 v[2:3], v[2:3], v[80:81] op_sel_hi:[1,0]
	v_cmp_lt_i32_e32 vcc, s11, v51
	v_mov_b32_e32 v41, v51
	s_or_b64 s[6:7], vcc, s[6:7]
	v_pk_add_f32 v[28:29], v[88:89], 1.0 op_sel_hi:[1,0]
	v_pk_add_f32 v[30:31], v[90:91], 1.0 op_sel_hi:[1,0]
	v_pk_fma_f32 v[24:25], v[24:25], v[28:29], v[92:93]
	v_pk_fma_f32 v[26:27], v[26:27], v[30:31], v[94:95]
	v_cvt_pk_bf16_f32 v24, v24, v25
	v_cvt_pk_bf16_f32 v25, v26, v27
	global_store_dwordx2 v[36:37], v[24:25], off offset:512
	v_lshl_add_u64 v[52:53], v[76:77], 0, v[42:43]
	v_pk_mul_f32 v[76:77], v[20:21], v[0:1]
	v_pk_add_f32 v[24:25], v[96:97], 1.0 op_sel_hi:[1,0]
	v_pk_add_f32 v[26:27], v[98:99], 1.0 op_sel_hi:[1,0]
	v_pk_fma_f32 v[8:9], v[8:9], v[24:25], v[100:101]
	v_pk_fma_f32 v[10:11], v[10:11], v[26:27], v[102:103]
	v_cvt_pk_bf16_f32 v8, v8, v9
	v_cvt_pk_bf16_f32 v9, v10, v11
	global_store_dwordx2 v[36:37], v[8:9], off offset:1024
	v_pk_mul_f32 v[78:79], v[22:23], v[2:3]
	v_pk_add_f32 v[52:53], v[104:105], 1.0 op_sel_hi:[1,0]
	v_pk_add_f32 v[54:55], v[106:107], 1.0 op_sel_hi:[1,0]
	v_pk_fma_f32 v[52:53], v[76:77], v[52:53], v[108:109]
	v_pk_fma_f32 v[54:55], v[78:79], v[54:55], v[110:111]
	v_cvt_pk_bf16_f32 v52, v52, v53
	v_cvt_pk_bf16_f32 v53, v54, v55
	global_store_dwordx2 v[36:37], v[52:53], off offset:1536
	v_lshl_add_u64 v[36:37], v[36:37], 0, s[4:5]
	v_mov_b32_e32 v0, v160
	v_mov_b32_e32 v1, v161
	v_mov_b32_e32 v30, v150
	v_mov_b32_e32 v31, v151
	v_mov_b32_e32 v28, v148
	v_mov_b32_e32 v29, v149
	v_mov_b32_e32 v26, v154
	v_mov_b32_e32 v27, v155
	v_mov_b32_e32 v24, v152
	v_mov_b32_e32 v25, v153
	v_mov_b32_e32 v10, v158
	v_mov_b32_e32 v11, v159
	v_mov_b32_e32 v8, v156
	v_mov_b32_e32 v9, v157
	v_mov_b32_e32 v2, v162
	v_mov_b32_e32 v3, v163
	s_andn2_b64 exec, exec, s[6:7]
	s_cbranch_execnz .LBB0_69
.Lpn_exit:
.LBB0_70:
	s_or_b64 exec, exec, s[0:1]
	s_waitcnt vmcnt(0) lgkmcnt(0)
	s_barrier
	s_mov_b64 s[0:1], exec
	v_readlane_b32 s4, v254, 7
	v_readlane_b32 s5, v254, 8
	s_and_b64 s[4:5], s[0:1], s[4:5]
	s_mov_b64 exec, s[4:5]
	s_cbranch_execz .LBB0_79
	s_mov_b64 s[6:7], exec
	v_mbcnt_lo_u32_b32 v0, s6, 0
	v_mbcnt_hi_u32_b32 v0, s7, v0
	v_cmp_eq_u32_e32 vcc, 0, v0
	s_and_saveexec_b64 s[4:5], vcc
	s_cbranch_execz .LBB0_73
	v_readlane_b32 s8, v254, 6
	s_lshl_b32 s8, s8, 8
	s_add_u32 s8, s44, s8
	s_addc_u32 s9, s45, 0
	s_bcnt1_i32_b64 s6, s[6:7]
	v_mov_b32_e32 v1, 0x1000
	v_mov_b32_e32 v2, s6
	global_atomic_add v1, v1, v2, s[8:9] offset:256 sc0
